# mixer phase: after the deferred gMLP pass the workgroup falls straight into the attention sweep (one phase re-entry instead of two)
# speedup vs baseline: 1.0021x; 1.0021x over previous
.LBB0_126:
	v_readlane_b32 s0, v252, 48
	v_readlane_b32 s1, v252, 49
	s_andn2_b64 vcc, exec, s[0:1]
	s_barrier
	s_cbranch_vccnz .LBB0_227
	v_readlane_b32 s0, v255, 61
	s_nop 3
	s_cmp_eq_u32 s0, 2
	s_cbranch_scc0 .Lgd_go
	s_mov_b32 s0, 3
	s_nop 0
	v_writelane_b32 v255, s0, 61
.Lgd_go:
	s_lshl_b64 s[0:1], s[94:95], 2
	v_readlane_b32 s2, v252, 25
	s_add_u32 s8, s2, s0
	v_readlane_b32 s0, v252, 26
	s_addc_u32 s9, s0, s1
	s_lshl_b32 s0, s94, 7
	v_ashrrev_i32_e32 v1, 6, v200
	s_ashr_i32 s1, s0, 31
	v_lshlrev_b32_e32 v0, 5, v1
	s_lshl_b64 s[0:1], s[0:1], 2
	v_readlane_b32 s2, v252, 27
	v_ashrrev_i32_e32 v203, 31, v0
	v_or_b32_e32 v202, v0, v157
	v_lshrrev_b32_e32 v0, 2, v200
	s_add_u32 s10, s2, s0
	v_readlane_b32 s0, v252, 28
	v_and_b32_e32 v0, 8, v0
	v_readlane_b32 s2, v253, 33
	s_addc_u32 s11, s0, s1
	v_cmp_eq_u32_e64 s[0:1], 0, v244
	v_lshl_add_u32 v195, v1, 2, s2
	v_lshlrev_b32_e32 v201, 8, v244
	v_lshlrev_b32_e32 v192, 1, v0
	v_readlane_b32 s20, v252, 47
	v_readlane_b32 s32, v255, 61
	s_nop 3
	s_cmp_lg_u32 s32, 3
	s_cbranch_scc1 .Lgd_first
	v_readlane_b32 s20, v255, 59
	s_nop 3
	s_cmpk_gt_i32 s20, 0x3ff
	s_cbranch_scc1 .LBB0_227
